# attention loop tail: the last P.V MFMAs issue before the next-tile LDS stash writes instead of after them
# speedup vs baseline: 1.0025x; 1.0025x over previous
; DI void attn_tile8(const Params& p, int bh, int qt, char* smem) {
;     ...
;     {
;       bf16x8 kf[2][4];
; #pragma unroll
;       for (int kb = 0; kb < 4; ++kb) kf[0][kb] = *(const bf16x8*)(Ks + (kb * 32 + lr) * 208 + lh * 16);
; #pragma unroll
;       for (int s = 0; s < 6; ++s) {
;         if (s < 5) {
; #pragma unroll
;           for (int kb = 0; kb < 4; ++kb) kf[(s + 1) & 1][kb] = *(const bf16x8*)(Ks + (kb * 32 + lr) * 208 + (s + 1) * 32 + lh * 16);
;         }
;         __builtin_amdgcn_sched_barrier(0);
;         __builtin_amdgcn_s_setprio(1);
; #pragma unroll
;         for (int kb = 0; kb < 4; ++kb) st[kb] = MFMA32(kf[s & 1][kb], qf[s], st[kb]);
;         __builtin_amdgcn_s_setprio(0);
;         __builtin_amdgcn_sched_barrier(0);
;       }
;     }
;     float mx = st[0][0];
; #pragma unroll
;     for (int kb = 0; kb < 4; ++kb)
; #pragma unroll
;       for (int i = 0; i < 16; ++i) mx = fmaxf(mx, st[kb][i]);
;     mx = fmaxf(mx, __shfl_xor(mx, 32));
;     const float mn = fmaxf(m, mx);
;     const float alpha = __builtin_amdgcn_exp2f(m - mn);
;     m = mn;
;     float ps = 0.f;
; #pragma unroll
;     for (int kb = 0; kb < 4; ++kb)
; #pragma unroll
;       for (int i = 0; i < 16; ++i) { st[kb][i] = __builtin_amdgcn_exp2f(st[kb][i] - mn); ps += st[kb][i]; }
;     lsum = lsum * alpha + ps;
; #pragma unroll
;     for (int i = 0; i < 16; ++i) { O[0][i] *= alpha; O[1][i] *= alpha; }
;     {
;       u32x4 vfr[2][2];
; #pragma unroll
;       for (int vb = 0; vb < 2; ++vb) {
;         const char* vp = Vs + (vb * 32 + lr) * VROW + (4 * lh) * 2;
;         const uint2 v0 = *(const uint2*)(vp);
;         const uint2 v1 = *(const uint2*)(vp + 16);
;         vfr[0][vb] = (u32x4){v0.x, v0.y, v1.x, v1.y};
;       }
; #pragma unroll
;       for (int step = 0; step < 8; ++step) {
;         const int kb = step >> 1, s2 = step & 1;
;         if (step < 7) {
;           const int kb2 = (step + 1) >> 1, s22 = (step + 1) & 1;
; #pragma unroll
;           for (int vb = 0; vb < 2; ++vb) {
;             const char* vp = Vs + (vb * 32 + lr) * VROW + (kb2 * 32 + 16 * s22 + 4 * lh) * 2;
;             const uint2 v0 = *(const uint2*)(vp);
;             const uint2 v1 = *(const uint2*)(vp + 16);
;             vfr[(step + 1) & 1][vb] = (u32x4){v0.x, v0.y, v1.x, v1.y};
;           }
;         }
;         u32x4 pk;
;         pk.x = pack2(st[kb][8 * s2 + 0], st[kb][8 * s2 + 1]);
.Lattn_noresc:
	ds_read_b128 v[180:183], v177 offset:0
	ds_read_b128 v[184:187], v177 offset:32
	ds_read_b128 v[188:191], v177 offset:64
	ds_read_b128 v[200:203], v177 offset:96
	v_mfma_f32_32x32x16_bf16 v[80:95], v[214:217], v[218:221], 0
	s_waitcnt lgkmcnt(3)
	v_mfma_f32_32x32x16_bf16 v[80:95], v[180:183], v[96:99], v[80:95]
	ds_read_b128 v[180:183], v177 offset:128
	s_waitcnt lgkmcnt(3)
	v_mfma_f32_32x32x16_bf16 v[80:95], v[184:187], v[100:103], v[80:95]
	ds_read_b128 v[184:187], v177 offset:160
	s_waitcnt lgkmcnt(3)
	v_mfma_f32_32x32x16_bf16 v[80:95], v[188:191], v[104:107], v[80:95]
	ds_read_b128 v[188:191], v177 offset:6656
	s_waitcnt lgkmcnt(3)
	v_mfma_f32_32x32x16_bf16 v[80:95], v[200:203], v[108:111], v[80:95]
	ds_read_b128 v[200:203], v177 offset:6688
	s_waitcnt lgkmcnt(3)
	v_mfma_f32_32x32x16_bf16 v[80:95], v[180:183], v[112:115], v[80:95]
	ds_read_b128 v[180:183], v177 offset:6720
	s_waitcnt lgkmcnt(3)
	v_mfma_f32_32x32x16_bf16 v[80:95], v[184:187], v[116:119], v[80:95]
	ds_read_b128 v[184:187], v177 offset:6752
	v_mfma_f32_32x32x16_bf16 v[64:79], v[214:217], v[218:221], 0
	s_waitcnt lgkmcnt(3)
	v_mfma_f32_32x32x16_bf16 v[64:79], v[188:191], v[96:99], v[64:79]
	ds_read_b128 v[188:191], v177 offset:6784
	s_waitcnt lgkmcnt(3)
	v_mfma_f32_32x32x16_bf16 v[64:79], v[200:203], v[100:103], v[64:79]
	ds_read_b128 v[200:203], v177 offset:6816
	s_waitcnt lgkmcnt(3)
	v_mfma_f32_32x32x16_bf16 v[64:79], v[180:183], v[104:107], v[64:79]
	ds_read_b128 v[180:183], v177 offset:13312
	s_nop 0
	v_max_f32_e32 v232, v80, v81
	v_max3_f32 v232, v232, v82, v83
	v_max3_f32 v232, v232, v84, v85
	v_max3_f32 v232, v232, v86, v87
	v_max3_f32 v232, v232, v88, v89
	v_max3_f32 v232, v232, v90, v91
	v_max3_f32 v232, v232, v92, v93
	v_max3_f32 v232, v232, v94, v95
	ds_bpermute_b32 v233, v175, v232
	v_exp_f32_e32 v80, v80
	v_exp_f32_e32 v81, v81
	v_exp_f32_e32 v82, v82
	v_exp_f32_e32 v83, v83
	s_waitcnt lgkmcnt(4)
	v_mfma_f32_32x32x16_bf16 v[64:79], v[184:187], v[108:111], v[64:79]
	ds_read_b128 v[184:187], v177 offset:13344
	v_exp_f32_e32 v84, v84
	v_exp_f32_e32 v85, v85
	v_exp_f32_e32 v86, v86
	v_exp_f32_e32 v87, v87
	v_exp_f32_e32 v88, v88
	v_exp_f32_e32 v89, v89
	v_exp_f32_e32 v90, v90
	v_exp_f32_e32 v91, v91
	v_exp_f32_e32 v92, v92
	v_exp_f32_e32 v93, v93
	v_exp_f32_e32 v94, v94
	v_exp_f32_e32 v95, v95
	s_waitcnt lgkmcnt(4)
	v_mfma_f32_32x32x16_bf16 v[64:79], v[188:191], v[112:115], v[64:79]
	ds_read_b128 v[188:191], v177 offset:13376
	v_add_f32_e32 v238, v238, v80
	v_add_f32_e32 v239, v239, v81
	v_add_f32_e32 v238, v238, v82
	v_add_f32_e32 v239, v239, v83
	v_add_f32_e32 v238, v238, v84
	v_add_f32_e32 v239, v239, v85
	v_add_f32_e32 v238, v238, v86
	v_add_f32_e32 v239, v239, v87
	v_add_f32_e32 v238, v238, v88
	v_add_f32_e32 v239, v239, v89
	v_add_f32_e32 v238, v238, v90
	v_add_f32_e32 v239, v239, v91
	s_waitcnt lgkmcnt(4)
	v_mfma_f32_32x32x16_bf16 v[64:79], v[200:203], v[116:119], v[64:79]
	ds_read_b128 v[200:203], v177 offset:13408
	v_add_f32_e32 v238, v238, v92
	v_add_f32_e32 v239, v239, v93
	v_add_f32_e32 v238, v238, v94
	v_add_f32_e32 v239, v239, v95
	v_cvt_pk_bf16_f32 v222, v80, v81
	v_cvt_pk_bf16_f32 v223, v82, v83
	v_cvt_pk_bf16_f32 v224, v84, v85
	v_cvt_pk_bf16_f32 v225, v86, v87
	v_cvt_pk_bf16_f32 v226, v88, v89
	v_cvt_pk_bf16_f32 v227, v90, v91
	v_cvt_pk_bf16_f32 v228, v92, v93
	v_cvt_pk_bf16_f32 v229, v94, v95
	ds_read2_b64 v[80:83], v199 offset0:0 offset1:2
	ds_read2_b64 v[84:87], v179 offset0:32 offset1:34
	ds_read2_b64 v[88:91], v199 offset0:4 offset1:6
	ds_read2_b64 v[92:95], v179 offset0:36 offset1:38
	v_mfma_f32_32x32x16_bf16 v[48:63], v[214:217], v[218:221], 0
	s_waitcnt lgkmcnt(8)
	v_mfma_f32_32x32x16_bf16 v[48:63], v[180:183], v[96:99], v[48:63]
	ds_read_b128 v[180:183], v177 offset:13440
	s_waitcnt lgkmcnt(7)
	v_mfma_f32_32x32x16_bf16 v[48:63], v[184:187], v[100:103], v[48:63]
	ds_read_b128 v[184:187], v177 offset:13472
	s_waitcnt lgkmcnt(5)
	v_mfma_f32_32x32x16_bf16 v[16:31], v[80:83], v[222:225], v[16:31]
	v_exp_f32_e32 v64, v64
	v_exp_f32_e32 v65, v65
	v_exp_f32_e32 v66, v66
	v_exp_f32_e32 v67, v67
	v_exp_f32_e32 v68, v68
	s_waitcnt lgkmcnt(4)
	v_mfma_f32_32x32x16_bf16 v[0:15], v[84:87], v[222:225], v[0:15]
	v_exp_f32_e32 v69, v69
	v_exp_f32_e32 v70, v70
	v_exp_f32_e32 v71, v71
	v_exp_f32_e32 v72, v72
	v_exp_f32_e32 v73, v73
	v_mfma_f32_32x32x16_bf16 v[48:63], v[188:191], v[104:107], v[48:63]
	ds_read_b128 v[188:191], v177 offset:19968
	v_exp_f32_e32 v74, v74
	v_exp_f32_e32 v75, v75
	v_exp_f32_e32 v76, v76
	v_exp_f32_e32 v77, v77
	v_exp_f32_e32 v78, v78
	v_mfma_f32_32x32x16_bf16 v[48:63], v[200:203], v[108:111], v[48:63]
	ds_read_b128 v[200:203], v177 offset:20000
	v_exp_f32_e32 v79, v79
	v_add_f32_e32 v238, v238, v64
	v_add_f32_e32 v239, v239, v65
	v_add_f32_e32 v238, v238, v66
	v_add_f32_e32 v239, v239, v67
	s_waitcnt lgkmcnt(5)
	v_mfma_f32_32x32x16_bf16 v[16:31], v[88:91], v[226:229], v[16:31]
	v_add_f32_e32 v238, v238, v68
	v_add_f32_e32 v239, v239, v69
	v_add_f32_e32 v238, v238, v70
	v_add_f32_e32 v239, v239, v71
	v_add_f32_e32 v238, v238, v72
	s_waitcnt lgkmcnt(4)
	v_mfma_f32_32x32x16_bf16 v[0:15], v[92:95], v[226:229], v[0:15]
	v_add_f32_e32 v239, v239, v73
	v_add_f32_e32 v238, v238, v74
	v_add_f32_e32 v239, v239, v75
	v_add_f32_e32 v238, v238, v76
	v_add_f32_e32 v239, v239, v77
	s_waitcnt lgkmcnt(3)
	v_mfma_f32_32x32x16_bf16 v[48:63], v[180:183], v[112:115], v[48:63]
	ds_read_b128 v[180:183], v177 offset:20032
	v_add_f32_e32 v238, v238, v78
	v_add_f32_e32 v239, v239, v79
	v_cvt_pk_bf16_f32 v222, v64, v65
	v_cvt_pk_bf16_f32 v223, v66, v67
	v_cvt_pk_bf16_f32 v224, v68, v69
	s_waitcnt lgkmcnt(3)
; DI void attn_tile8(const Params& p, int bh, int qt, char* smem) {
;     ...
;   auto store_tiles = [&](int st) {
;     char* Ks = smem + st * STAGE;
;     char* Vs = Ks + VOFF;
; #pragma unroll
;     for (int i = 0; i < 3; ++i) {
;       const int idx = tid + 512 * i, key = idx / 12, ch = idx % 12;
;       *(u32x4*)(Ks + key * 208 + ch * 16) = rk[i];
;     }
; #pragma unroll
;     for (int i = 0; i < 2; ++i) {
;       const int idx = tid + 512 * i, vd = idx >> 4, ch = idx & 15;
;     ...
;     for (int kb = 0; kb < 4; ++kb)
; #pragma unroll
;       for (int i = 0; i < 16; ++i) { st[kb][i] = __builtin_amdgcn_exp2f(st[kb][i] - mn); ps += st[kb][i]; }
;     lsum = lsum * alpha + ps;
; #pragma unroll
;     for (int i = 0; i < 16; ++i) { O[0][i] *= alpha; O[1][i] *= alpha; }
;     {
;       u32x4 vfr[2][2];
; #pragma unroll
;       for (int vb = 0; vb < 2; ++vb) {
;         const char* vp = Vs + (vb * 32 + lr) * VROW + (4 * lh) * 2;
;         const uint2 v0 = *(const uint2*)(vp);
;         const uint2 v1 = *(const uint2*)(vp + 16);
;         vfr[0][vb] = (u32x4){v0.x, v0.y, v1.x, v1.y};
;       }
; #pragma unroll
;       for (int step = 0; step < 8; ++step) {
;         const int kb = step >> 1, s2 = step & 1;
;         if (step < 7) {
;           const int kb2 = (step + 1) >> 1, s22 = (step + 1) & 1;
; #pragma unroll
;           for (int vb = 0; vb < 2; ++vb) {
;             const char* vp = Vs + (vb * 32 + lr) * VROW + (kb2 * 32 + 16 * s22 + 4 * lh) * 2;
;             const uint2 v0 = *(const uint2*)(vp);
;             const uint2 v1 = *(const uint2*)(vp + 16);
;             vfr[(step + 1) & 1][vb] = (u32x4){v0.x, v0.y, v1.x, v1.y};
;           }
;         }
;         u32x4 pk;
;         pk.x = pack2(st[kb][8 * s2 + 0], st[kb][8 * s2 + 1]);
;         pk.y = pack2(st[kb][8 * s2 + 2], st[kb][8 * s2 + 3]);
;         pk.z = pack2(st[kb][8 * s2 + 4], st[kb][8 * s2 + 5]);
;         pk.w = pack2(st[kb][8 * s2 + 6], st[kb][8 * s2 + 7]);
;         const bf16x8 bfrag = __builtin_bit_cast(bf16x8, pk);
;         __builtin_amdgcn_sched_barrier(0);
;         O[0] = MFMA32(__builtin_bit_cast(bf16x8, vfr[step & 1][0]), bfrag, O[0]);
;         O[1] = MFMA32(__builtin_bit_cast(bf16x8, vfr[step & 1][1]), bfrag, O[1]);
;         __builtin_amdgcn_sched_barrier(0);
;       }
;     }
;     if (more) store_tiles((kt + 1) & 1);
;     __syncthreads();
;   }
	v_mfma_f32_32x32x16_bf16 v[48:63], v[184:187], v[116:119], v[48:63]
	ds_read_b128 v[184:187], v177 offset:20064
	v_cvt_pk_bf16_f32 v225, v70, v71
	v_cvt_pk_bf16_f32 v226, v72, v73
	v_cvt_pk_bf16_f32 v227, v74, v75
	v_cvt_pk_bf16_f32 v228, v76, v77
	v_cvt_pk_bf16_f32 v229, v78, v79
	ds_read2_b64 v[64:67], v199 offset0:8 offset1:10
	ds_read2_b64 v[68:71], v179 offset0:40 offset1:42
	ds_read2_b64 v[72:75], v199 offset0:12 offset1:14
	ds_read2_b64 v[76:79], v179 offset0:44 offset1:46
	v_mfma_f32_32x32x16_bf16 v[32:47], v[214:217], v[218:221], 0
	s_waitcnt lgkmcnt(7)
	v_mfma_f32_32x32x16_bf16 v[32:47], v[188:191], v[96:99], v[32:47]
	ds_read_b128 v[188:191], v177 offset:20096
	s_waitcnt lgkmcnt(7)
	v_mfma_f32_32x32x16_bf16 v[32:47], v[200:203], v[100:103], v[32:47]
	ds_read_b128 v[200:203], v177 offset:20128
	s_waitcnt lgkmcnt(5)
	v_mfma_f32_32x32x16_bf16 v[16:31], v[64:67], v[222:225], v[16:31]
	v_exp_f32_e32 v48, v48
	v_exp_f32_e32 v49, v49
	v_exp_f32_e32 v50, v50
	v_exp_f32_e32 v51, v51
	v_exp_f32_e32 v52, v52
	s_waitcnt lgkmcnt(4)
	v_mfma_f32_32x32x16_bf16 v[0:15], v[68:71], v[222:225], v[0:15]
	v_exp_f32_e32 v53, v53
	v_exp_f32_e32 v54, v54
	v_exp_f32_e32 v55, v55
	v_exp_f32_e32 v56, v56
	v_exp_f32_e32 v57, v57
	v_mfma_f32_32x32x16_bf16 v[32:47], v[180:183], v[104:107], v[32:47]
	v_exp_f32_e32 v58, v58
	v_exp_f32_e32 v59, v59
	v_exp_f32_e32 v60, v60
	v_exp_f32_e32 v61, v61
	v_exp_f32_e32 v62, v62
	v_mfma_f32_32x32x16_bf16 v[32:47], v[184:187], v[108:111], v[32:47]
	v_exp_f32_e32 v63, v63
	v_add_f32_e32 v238, v238, v48
	v_add_f32_e32 v239, v239, v49
	v_add_f32_e32 v238, v238, v50
	v_add_f32_e32 v239, v239, v51
	s_waitcnt lgkmcnt(3)
	v_mfma_f32_32x32x16_bf16 v[16:31], v[72:75], v[226:229], v[16:31]
	v_add_f32_e32 v238, v238, v52
	v_add_f32_e32 v239, v239, v53
	v_add_f32_e32 v238, v238, v54
	v_add_f32_e32 v239, v239, v55
	v_add_f32_e32 v238, v238, v56
	s_waitcnt lgkmcnt(2)
	v_mfma_f32_32x32x16_bf16 v[0:15], v[76:79], v[226:229], v[0:15]
	v_add_f32_e32 v239, v239, v57
	v_add_f32_e32 v238, v238, v58
	v_add_f32_e32 v239, v239, v59
	v_add_f32_e32 v238, v238, v60
	v_add_f32_e32 v239, v239, v61
	s_waitcnt lgkmcnt(1)
	v_mfma_f32_32x32x16_bf16 v[32:47], v[188:191], v[112:115], v[32:47]
	v_add_f32_e32 v238, v238, v62
	v_add_f32_e32 v239, v239, v63
	v_cvt_pk_bf16_f32 v222, v48, v49
	v_cvt_pk_bf16_f32 v223, v50, v51
	v_cvt_pk_bf16_f32 v224, v52, v53
	s_waitcnt lgkmcnt(0)
	v_mfma_f32_32x32x16_bf16 v[32:47], v[200:203], v[116:119], v[32:47]
	v_cvt_pk_bf16_f32 v225, v54, v55
	v_cvt_pk_bf16_f32 v226, v56, v57
	v_cvt_pk_bf16_f32 v227, v58, v59
	v_cvt_pk_bf16_f32 v228, v60, v61
	v_cvt_pk_bf16_f32 v229, v62, v63
	ds_read2_b64 v[48:51], v199 offset0:16 offset1:18
	ds_read2_b64 v[52:55], v179 offset0:48 offset1:50
	ds_read2_b64 v[56:59], v199 offset0:20 offset1:22
	ds_read2_b64 v[60:63], v179 offset0:52 offset1:54
	s_waitcnt lgkmcnt(3)
	v_mfma_f32_32x32x16_bf16 v[16:31], v[48:51], v[222:225], v[16:31]
	s_nop 0
	v_exp_f32_e32 v32, v32
	v_exp_f32_e32 v33, v33
	v_exp_f32_e32 v34, v34
	v_exp_f32_e32 v35, v35
	v_exp_f32_e32 v36, v36
	v_exp_f32_e32 v37, v37
	v_exp_f32_e32 v38, v38
	v_exp_f32_e32 v39, v39
	v_exp_f32_e32 v40, v40
	v_exp_f32_e32 v41, v41
	s_waitcnt lgkmcnt(2)
	v_mfma_f32_32x32x16_bf16 v[0:15], v[52:55], v[222:225], v[0:15]
	v_exp_f32_e32 v42, v42
	v_exp_f32_e32 v43, v43
	v_exp_f32_e32 v44, v44
	v_exp_f32_e32 v45, v45
	v_exp_f32_e32 v46, v46
	v_exp_f32_e32 v47, v47
	v_add_f32_e32 v238, v238, v32
	v_add_f32_e32 v239, v239, v33
	v_add_f32_e32 v238, v238, v34
	v_add_f32_e32 v239, v239, v35
	s_waitcnt lgkmcnt(1)
	v_mfma_f32_32x32x16_bf16 v[16:31], v[56:59], v[226:229], v[16:31]
	v_add_f32_e32 v238, v238, v36
	v_add_f32_e32 v239, v239, v37
	v_add_f32_e32 v238, v238, v38
	v_add_f32_e32 v239, v239, v39
	v_add_f32_e32 v238, v238, v40
	v_add_f32_e32 v239, v239, v41
	v_add_f32_e32 v238, v238, v42
	v_add_f32_e32 v239, v239, v43
	v_add_f32_e32 v238, v238, v44
	v_add_f32_e32 v239, v239, v45
	s_waitcnt lgkmcnt(0)
	v_mfma_f32_32x32x16_bf16 v[0:15], v[60:63], v[226:229], v[0:15]
	v_add_f32_e32 v238, v238, v46
	v_add_f32_e32 v239, v239, v47
	v_cvt_pk_bf16_f32 v222, v32, v33
	v_cvt_pk_bf16_f32 v223, v34, v35
	v_cvt_pk_bf16_f32 v224, v36, v37
	v_cvt_pk_bf16_f32 v225, v38, v39
	v_cvt_pk_bf16_f32 v226, v40, v41
	v_cvt_pk_bf16_f32 v227, v42, v43
	v_cvt_pk_bf16_f32 v228, v44, v45
	v_cvt_pk_bf16_f32 v229, v46, v47
	ds_read2_b64 v[32:35], v199 offset0:24 offset1:26
	ds_read2_b64 v[36:39], v179 offset0:56 offset1:58
	ds_read2_b64 v[40:43], v199 offset0:28 offset1:30
	ds_read2_b64 v[44:47], v179 offset0:60 offset1:62
	s_waitcnt lgkmcnt(3)
	v_mfma_f32_32x32x16_bf16 v[16:31], v[32:35], v[222:225], v[16:31]
	s_waitcnt lgkmcnt(2)
	v_mfma_f32_32x32x16_bf16 v[0:15], v[36:39], v[222:225], v[0:15]
	s_waitcnt lgkmcnt(1)
	v_mfma_f32_32x32x16_bf16 v[16:31], v[40:43], v[226:229], v[16:31]
	s_waitcnt lgkmcnt(0)
	v_mfma_f32_32x32x16_bf16 v[0:15], v[44:47], v[226:229], v[0:15]
	s_bitcmp1_b32 s23, 0
	s_cselect_b32 s20, 0xaa00, 0
	v_add3_u32 v213, s20, v147, v144
	s_waitcnt vmcnt(4)
	ds_write_b128 v213, v[120:123]
	v_add3_u32 v213, s20, v149, v146
	s_waitcnt vmcnt(3)
	ds_write_b128 v213, v[124:127]
	v_add3_u32 v213, s20, v151, v148
	s_waitcnt vmcnt(2)
	ds_write_b128 v213, v[128:131]
	v_add_u32_e32 v213, s20, v173
	s_movk_i32 s21, 0x6800
	v_add3_u32 v213, v213, v150, s21
	s_waitcnt vmcnt(1)
	ds_write2_b64 v213, v[132:133], v[134:135] offset1:1
	v_add_u32_e32 v213, s20, v174
	v_add3_u32 v213, v213, v150, s21
	s_waitcnt vmcnt(0)
	ds_write2_b64 v213, v[136:137], v[138:139] offset1:1
	s_mov_b64 s[20:21], 0x100
	s_add_u32 s18, s18, 0x20000
	v_lshl_add_u64 v[160:161], v[160:161], 0, s[20:21]
	v_lshl_add_u64 v[162:163], v[162:163], 0, s[20:21]
	s_addc_u32 s19, s19, 0
	s_mov_b64 s[20:21], 0x2000
	s_cmp_lg_u32 s18, 0x440000
	v_lshl_add_u64 v[152:153], v[152:153], 0, s[20:21]
	s_waitcnt lgkmcnt(0)
	s_barrier
	s_cbranch_scc0 .Lattn_exit
	s_mov_b32 s31, s23
	s_branch .Lattn_loop
